# v38 + hgrn step-A section-B head: e^{bref} vector fetched early, first S'->bf16 group under the first row-sum bpermute
# baseline (speedup 1.0000x reference)
.LBB0_525:
	s_min_u32 s54, s91, 28
	s_lshl_b32 s92, s91, 6
	s_lshl_b32 s54, s54, 6
	s_or_b32 s66, s92, 64
	s_add_i32 s58, s54, 0xc0
	s_add_u32 s54, s62, s58
	s_addc_u32 s55, s63, 0
	v_add_u32_e32 v32, v175, v162
	s_add_u32 s58, s60, s58
	ds_write_b128 v32, v[16:19]
	v_add_u32_e32 v16, v175, v163
	s_addc_u32 s59, 0, 0
	ds_write_b128 v16, v[20:23]
	v_lshl_add_u64 v[16:17], v[88:89], 0, s[66:67]
	s_add_u32 s72, s54, s86
	v_lshlrev_b64 v[16:17], 8, v[16:17]
	s_addc_u32 s73, s55, 0
	v_lshl_add_u64 v[16:17], v[90:91], 0, v[16:17]
	s_lshl_b64 s[72:73], s[72:73], 8
	global_load_dwordx2 v[100:101], v[16:17], off
	global_load_dwordx2 v[98:99], v[16:17], off offset:32
	global_load_dwordx2 v[96:97], v[16:17], off offset:64
	global_load_dwordx2 v[94:95], v[16:17], off offset:96
	v_lshl_add_u64 v[16:17], v[70:71], 0, s[72:73]
	s_lshl_b64 s[58:59], s[58:59], 11
	global_load_dword v194, v[16:17], off
	v_lshl_add_u64 v[16:17], v[72:73], 0, s[58:59]
	s_or_b32 s58, s72, 0x100
	s_mov_b32 s59, s73
	v_lshl_add_u64 v[18:19], v[70:71], 0, s[58:59]
	s_or_b32 s58, s72, 0x200
	global_load_dword v200, v[16:17], off
	global_load_dword v186, v[18:19], off
	global_load_dword v198, v[16:17], off offset:2048
	v_lshl_add_u64 v[18:19], v[70:71], 0, s[58:59]
	global_load_dword v181, v[18:19], off
	v_add_co_u32_e32 v18, vcc, s61, v16
	s_or_b32 s58, s72, 0x300
	s_nop 0
	v_addc_co_u32_e32 v19, vcc, 0, v17, vcc
	v_add_co_u32_e32 v20, vcc, s87, v16
	v_lshl_add_u64 v[22:23], v[70:71], 0, s[58:59]
	s_nop 0
	v_addc_co_u32_e32 v21, vcc, 0, v17, vcc
	s_or_b32 s58, s72, 0x400
	global_load_dword v201, v[20:21], off offset:-4096
	global_load_dword v179, v[22:23], off
	global_load_dword v185, v[18:19], off offset:2048
	v_lshl_add_u64 v[18:19], v[70:71], 0, s[58:59]
	s_or_b32 s58, s72, 0x500
	global_load_dword v177, v[18:19], off
	global_load_dword v196, v[20:21], off
	v_lshl_add_u64 v[18:19], v[70:71], 0, s[58:59]
	s_or_b32 s58, s72, 0x600
	v_add_co_u32_e32 v16, vcc, s88, v16
	global_load_dword v173, v[18:19], off
	global_load_dword v187, v[20:21], off offset:2048
	v_lshl_add_u64 v[18:19], v[70:71], 0, s[58:59]
	v_addc_co_u32_e32 v17, vcc, 0, v17, vcc
	s_or_b32 s72, s72, 0x700
	global_load_dword v166, v[18:19], off
	global_load_dword v167, v[16:17], off
	v_lshl_add_u64 v[18:19], v[70:71], 0, s[72:73]
	global_load_dword v164, v[18:19], off
	global_load_dword v165, v[16:17], off offset:2048
	v_mov_b32_e32 v17, s55
	v_or_b32_e32 v16, s54, v93
	v_lshl_add_u64 v[20:21], s[54:55], 0, v[68:69]
	v_lshlrev_b64 v[16:17], 8, v[16:17]
	v_lshlrev_b64 v[20:21], 8, v[20:21]
	v_lshl_add_u64 v[16:17], v[74:75], 0, v[16:17]
	v_lshl_add_u64 v[20:21], v[74:75], 0, v[20:21]
	global_load_dwordx4 v[16:19], v[16:17], off
	s_nop 0
	global_load_dwordx4 v[20:23], v[20:21], off
	ds_read_b128 v[56:59], v218
	ds_read_b128 v[48:51], v218 offset:64
	ds_read_b128 v[44:47], v218 offset:128
	ds_read_b128 v[40:43], v218 offset:192
	ds_read_b128 v[36:39], v204 offset:17408
	ds_read_b128 v[228:231], v204 offset:17472
	ds_read_b128 v[232:235], v204 offset:17536
	ds_read_b128 v[236:239], v204 offset:17600
	s_waitcnt lgkmcnt(3)
	v_mfma_f32_16x16x32_bf16 v[32:35], v[36:39], v[56:59], 0
	s_waitcnt lgkmcnt(2)
	v_mfma_f32_16x16x32_bf16 v[32:35], v[228:231], v[48:51], v[32:35]
	s_waitcnt lgkmcnt(1)
	v_mfma_f32_16x16x32_bf16 v[32:35], v[232:235], v[44:47], v[32:35]
	s_waitcnt lgkmcnt(0)
	v_mfma_f32_16x16x32_bf16 v[32:35], v[236:239], v[40:43], v[32:35]
	ds_read_b128 v[36:39], v204 offset:21760
	ds_read_b128 v[228:231], v204 offset:21824
	ds_read_b128 v[232:235], v204 offset:21888
	ds_read_b128 v[236:239], v204 offset:21952
	s_nop 3
	v_cndmask_b32_e64 v52, 0, v32, s[18:19]
	v_cndmask_b32_e64 v53, 0, v33, s[20:21]
	v_cndmask_b32_e64 v54, 0, v34, s[22:23]
	v_cndmask_b32_e64 v55, 0, v35, s[24:25]
	v_cvt_pk_bf16_f32 v64, v52, v53
	v_cvt_pk_bf16_f32 v65, v54, v55
	s_waitcnt lgkmcnt(3)
	v_mfma_f32_16x16x32_bf16 v[32:35], v[36:39], v[56:59], 0
	s_waitcnt lgkmcnt(2)
	v_mfma_f32_16x16x32_bf16 v[32:35], v[228:231], v[48:51], v[32:35]
	s_waitcnt lgkmcnt(1)
	v_mfma_f32_16x16x32_bf16 v[32:35], v[232:235], v[44:47], v[32:35]
	s_waitcnt lgkmcnt(0)
	v_mfma_f32_16x16x32_bf16 v[32:35], v[236:239], v[40:43], v[32:35]
	ds_read_b128 v[36:39], v204 offset:26112
	ds_read_b128 v[228:231], v204 offset:26176
	ds_read_b128 v[232:235], v204 offset:26240
	ds_read_b128 v[236:239], v204 offset:26304
	s_nop 3
	v_cndmask_b32_e64 v60, 0, v32, s[26:27]
	v_cndmask_b32_e64 v61, 0, v33, s[28:29]
	v_cndmask_b32_e64 v62, 0, v34, s[30:31]
	v_cndmask_b32_e64 v63, 0, v35, s[34:35]
	v_cvt_pk_bf16_f32 v66, v60, v61
	v_cvt_pk_bf16_f32 v67, v62, v63
	s_waitcnt lgkmcnt(3)
	v_mfma_f32_16x16x32_bf16 v[32:35], v[36:39], v[56:59], 0
	s_waitcnt lgkmcnt(2)
	v_mfma_f32_16x16x32_bf16 v[32:35], v[228:231], v[48:51], v[32:35]
	s_waitcnt lgkmcnt(1)
	v_mfma_f32_16x16x32_bf16 v[32:35], v[232:235], v[44:47], v[32:35]
	s_waitcnt lgkmcnt(0)
	v_mfma_f32_16x16x32_bf16 v[32:35], v[236:239], v[40:43], v[32:35]
	ds_read_b128 v[36:39], v204 offset:30464
	ds_read_b128 v[228:231], v204 offset:30528
	ds_read_b128 v[232:235], v204 offset:30592
	ds_read_b128 v[236:239], v204 offset:30656
	s_nop 3
	v_cndmask_b32_e64 v86, 0, v32, s[36:37]
	v_cndmask_b32_e64 v149, 0, v33, s[38:39]
	v_cndmask_b32_e64 v150, 0, v34, s[40:41]
	v_cndmask_b32_e64 v151, 0, v35, s[42:43]
	v_cvt_pk_bf16_f32 v60, v86, v149
	v_cvt_pk_bf16_f32 v61, v150, v151
	v_add_u32_e32 v86, v178, v203
	s_waitcnt lgkmcnt(3)
	v_mfma_f32_16x16x32_bf16 v[32:35], v[36:39], v[56:59], 0
	s_waitcnt lgkmcnt(2)
	v_mfma_f32_16x16x32_bf16 v[32:35], v[228:231], v[48:51], v[32:35]
	s_waitcnt lgkmcnt(1)
	v_mfma_f32_16x16x32_bf16 v[32:35], v[232:235], v[44:47], v[32:35]
	s_waitcnt lgkmcnt(0)
	v_mfma_f32_16x16x32_bf16 v[32:35], v[236:239], v[40:43], v[32:35]
	ds_read_b64_tr_b16 v[150:151], v205 offset:43520
	ds_read_b64_tr_b16 v[152:153], v205 offset:47872
	ds_read_b128 v[228:231], v219
	ds_read_b128 v[232:235], v219 offset:64
	ds_read_b128 v[236:239], v219 offset:128
	ds_read_b128 v[240:243], v219 offset:192
	s_nop 1
	v_cndmask_b32_e64 v32, 0, v32, s[44:45]
	v_cndmask_b32_e64 v33, 0, v33, s[46:47]
	v_cndmask_b32_e64 v34, 0, v34, s[48:49]
	v_cndmask_b32_e64 v35, 0, v35, s[50:51]
	v_cvt_pk_bf16_f32 v62, v32, v33
	v_cvt_pk_bf16_f32 v63, v34, v35
	ds_read_b64_tr_b16 v[32:33], v205 offset:34816
	ds_read_b64_tr_b16 v[34:35], v205 offset:39168
	s_waitcnt lgkmcnt(0)
	v_mfma_f32_16x16x32_bf16 v[32:35], v[32:35], v[64:67], 0
	ds_read_b64_tr_b16 v[36:37], v206 offset:34816
	ds_read_b64_tr_b16 v[38:39], v206 offset:39168
	v_mfma_f32_16x16x32_bf16 v[32:35], v[150:153], v[60:63], v[32:35]
	ds_read_b64_tr_b16 v[150:151], v206 offset:43520
	ds_read_b64_tr_b16 v[152:153], v206 offset:47872
	v_mfma_f32_16x16x32_bf16 v[32:35], v[228:231], v[56:59], v[32:35]
	ds_read_b128 v[228:231], v220
	v_mfma_f32_16x16x32_bf16 v[32:35], v[232:235], v[48:51], v[32:35]
	ds_read_b128 v[232:235], v220 offset:64
	v_mfma_f32_16x16x32_bf16 v[32:35], v[236:239], v[44:47], v[32:35]
	ds_read_b128 v[236:239], v220 offset:128
	v_mfma_f32_16x16x32_bf16 v[32:35], v[240:243], v[40:43], v[32:35]
	ds_read_b128 v[240:243], v220 offset:192
	s_waitcnt lgkmcnt(6)
	v_mfma_f32_16x16x32_bf16 v[36:39], v[36:39], v[64:67], 0
	ds_read_b64_tr_b16 v[52:53], v207 offset:34816
	ds_read_b64_tr_b16 v[54:55], v207 offset:39168
	s_waitcnt lgkmcnt(6)
	v_mfma_f32_16x16x32_bf16 v[36:39], v[150:153], v[60:63], v[36:39]
	ds_read_b64_tr_b16 v[150:151], v207 offset:43520
	ds_read_b64_tr_b16 v[152:153], v207 offset:47872
	s_waitcnt lgkmcnt(7)
	v_mfma_f32_16x16x32_bf16 v[36:39], v[228:231], v[56:59], v[36:39]
	ds_read_b128 v[228:231], v221
	s_waitcnt lgkmcnt(7)
	v_mfma_f32_16x16x32_bf16 v[36:39], v[232:235], v[48:51], v[36:39]
	ds_read_b128 v[232:235], v221 offset:64
	s_waitcnt lgkmcnt(7)
	v_mfma_f32_16x16x32_bf16 v[36:39], v[236:239], v[44:47], v[36:39]
	ds_read_b128 v[236:239], v221 offset:128
	s_waitcnt lgkmcnt(7)
	v_mfma_f32_16x16x32_bf16 v[36:39], v[240:243], v[40:43], v[36:39]
	ds_read_b128 v[240:243], v221 offset:192
	s_waitcnt lgkmcnt(6)
	v_mfma_f32_16x16x32_bf16 v[52:55], v[52:55], v[64:67], 0
	ds_read_b64_tr_b16 v[244:245], v208 offset:34816
	ds_read_b64_tr_b16 v[246:247], v208 offset:39168
	s_waitcnt lgkmcnt(6)
	v_mfma_f32_16x16x32_bf16 v[52:55], v[150:153], v[60:63], v[52:55]
	ds_read_b64_tr_b16 v[150:151], v208 offset:43520
	ds_read_b64_tr_b16 v[152:153], v208 offset:47872
	s_waitcnt lgkmcnt(7)
	v_mfma_f32_16x16x32_bf16 v[52:55], v[228:231], v[56:59], v[52:55]
	ds_read_b128 v[228:231], v222
	s_waitcnt lgkmcnt(7)
	v_mfma_f32_16x16x32_bf16 v[52:55], v[232:235], v[48:51], v[52:55]
	ds_read_b128 v[232:235], v222 offset:64
	s_waitcnt lgkmcnt(7)
	v_mfma_f32_16x16x32_bf16 v[52:55], v[236:239], v[44:47], v[52:55]
	ds_read_b128 v[236:239], v222 offset:128
	s_waitcnt lgkmcnt(7)
	v_mfma_f32_16x16x32_bf16 v[52:55], v[240:243], v[40:43], v[52:55]
	ds_read_b128 v[240:243], v222 offset:192
	s_waitcnt lgkmcnt(6)
	v_mfma_f32_16x16x32_bf16 v[64:67], v[244:247], v[64:67], 0
	s_waitcnt lgkmcnt(4)
	v_mfma_f32_16x16x32_bf16 v[64:67], v[150:153], v[60:63], v[64:67]
	ds_read_b64_tr_b16 v[60:61], v209 offset:17408
	ds_read_b64_tr_b16 v[62:63], v209 offset:18496
	s_waitcnt lgkmcnt(5)
	v_mfma_f32_16x16x32_bf16 v[64:67], v[228:231], v[56:59], v[64:67]
	ds_read_b128 v[56:59], v182
	s_waitcnt lgkmcnt(5)
	v_mfma_f32_16x16x32_bf16 v[64:67], v[232:235], v[48:51], v[64:67]
	ds_read_b64_tr_b16 v[48:49], v209 offset:26112
	ds_read_b64_tr_b16 v[50:51], v209 offset:27200
	s_waitcnt lgkmcnt(6)
	v_mfma_f32_16x16x32_bf16 v[64:67], v[236:239], v[44:47], v[64:67]
	ds_read_b128 v[44:47], v180
	s_waitcnt lgkmcnt(6)
	v_mfma_f32_16x16x32_bf16 v[40:43], v[240:243], v[40:43], v[64:67]
	ds_read_b64_tr_b16 v[244:245], v86 offset:34816
	ds_read_b64_tr_b16 v[246:247], v86 offset:35904
	ds_read_b64_tr_b16 v[228:229], v86 offset:34848
	ds_read_b64_tr_b16 v[230:231], v86 offset:35936
	ds_read_b64_tr_b16 v[150:151], v86 offset:43520
	ds_read_b64_tr_b16 v[152:153], v86 offset:44608
	ds_read_b64_tr_b16 v[240:241], v86 offset:43552
	ds_read_b64_tr_b16 v[242:243], v86 offset:44640
	s_waitcnt lgkmcnt(6)
	v_mfma_f32_16x16x32_bf16 v[64:67], v[60:63], v[244:247], 0
	s_waitcnt lgkmcnt(4)
	v_mfma_f32_16x16x32_bf16 v[236:239], v[60:63], v[228:231], 0
	s_waitcnt lgkmcnt(2)
	v_mfma_f32_16x16x32_bf16 v[64:67], v[48:51], v[150:153], v[64:67]
	s_waitcnt lgkmcnt(0)
	v_mfma_f32_16x16x32_bf16 v[236:239], v[48:51], v[240:243], v[236:239]
	ds_read_b64_tr_b16 v[244:245], v86 offset:34880
	ds_read_b64_tr_b16 v[246:247], v86 offset:35968
	ds_read_b64_tr_b16 v[228:229], v86 offset:34912
	ds_read_b64_tr_b16 v[230:231], v86 offset:36000
	ds_read_b64_tr_b16 v[150:151], v86 offset:43584
	ds_read_b64_tr_b16 v[152:153], v86 offset:44672
	ds_read_b64_tr_b16 v[240:241], v86 offset:43616
	ds_read_b64_tr_b16 v[242:243], v86 offset:44704
	s_nop 3
	v_pk_mul_f32 v[66:67], v[58:59], v[66:67]
	v_pk_mul_f32 v[64:65], v[56:57], v[64:65]
	v_pk_fma_f32 v[104:105], v[104:105], v[46:47], v[66:67]
	v_pk_fma_f32 v[102:103], v[102:103], v[44:45], v[64:65]
	v_pk_mul_f32 v[238:239], v[58:59], v[238:239]
	v_pk_mul_f32 v[236:237], v[56:57], v[236:237]
	v_pk_fma_f32 v[114:115], v[114:115], v[46:47], v[238:239]
	v_pk_fma_f32 v[108:109], v[108:109], v[44:45], v[236:237]
	s_waitcnt lgkmcnt(6)
	v_mfma_f32_16x16x32_bf16 v[64:67], v[60:63], v[244:247], 0
	s_waitcnt lgkmcnt(4)
	v_mfma_f32_16x16x32_bf16 v[236:239], v[60:63], v[228:231], 0
	s_waitcnt lgkmcnt(2)
	v_mfma_f32_16x16x32_bf16 v[64:67], v[48:51], v[150:153], v[64:67]
	s_waitcnt lgkmcnt(0)
	v_mfma_f32_16x16x32_bf16 v[236:239], v[48:51], v[240:243], v[236:239]
	ds_read_b64_tr_b16 v[244:245], v86 offset:34944
	ds_read_b64_tr_b16 v[246:247], v86 offset:36032
	ds_read_b64_tr_b16 v[228:229], v86 offset:34976
	ds_read_b64_tr_b16 v[230:231], v86 offset:36064
	ds_read_b64_tr_b16 v[150:151], v86 offset:43648
	ds_read_b64_tr_b16 v[152:153], v86 offset:44736
	ds_read_b64_tr_b16 v[240:241], v86 offset:43680
	ds_read_b64_tr_b16 v[242:243], v86 offset:44768
	s_nop 3
	v_pk_mul_f32 v[66:67], v[58:59], v[66:67]
	v_pk_mul_f32 v[64:65], v[56:57], v[64:65]
	v_pk_fma_f32 v[112:113], v[112:113], v[46:47], v[66:67]
	v_pk_fma_f32 v[106:107], v[106:107], v[44:45], v[64:65]
	v_pk_mul_f32 v[238:239], v[58:59], v[238:239]
	v_pk_mul_f32 v[236:237], v[56:57], v[236:237]
	v_pk_fma_f32 v[118:119], v[118:119], v[46:47], v[238:239]
	v_pk_fma_f32 v[110:111], v[110:111], v[44:45], v[236:237]
	s_waitcnt lgkmcnt(6)
	v_mfma_f32_16x16x32_bf16 v[64:67], v[60:63], v[244:247], 0
	s_waitcnt lgkmcnt(4)
	v_mfma_f32_16x16x32_bf16 v[236:239], v[60:63], v[228:231], 0
	s_waitcnt lgkmcnt(2)
	v_mfma_f32_16x16x32_bf16 v[64:67], v[48:51], v[150:153], v[64:67]
	s_waitcnt lgkmcnt(0)
	v_mfma_f32_16x16x32_bf16 v[236:239], v[48:51], v[240:243], v[236:239]
	ds_read_b64_tr_b16 v[244:245], v86 offset:35008
	ds_read_b64_tr_b16 v[246:247], v86 offset:36096
	ds_read_b64_tr_b16 v[228:229], v86 offset:35040
	ds_read_b64_tr_b16 v[230:231], v86 offset:36128
	ds_read_b64_tr_b16 v[150:151], v86 offset:43712
	ds_read_b64_tr_b16 v[152:153], v86 offset:44800
	ds_read_b64_tr_b16 v[240:241], v86 offset:43744
	ds_read_b64_tr_b16 v[242:243], v86 offset:44832
	s_nop 3
	v_pk_mul_f32 v[66:67], v[58:59], v[66:67]
	v_pk_mul_f32 v[64:65], v[56:57], v[64:65]
	v_pk_fma_f32 v[122:123], v[122:123], v[46:47], v[66:67]
	v_pk_fma_f32 v[116:117], v[116:117], v[44:45], v[64:65]
	v_pk_mul_f32 v[238:239], v[58:59], v[238:239]
	v_pk_mul_f32 v[236:237], v[56:57], v[236:237]
	v_pk_fma_f32 v[126:127], v[126:127], v[46:47], v[238:239]
	v_pk_fma_f32 v[120:121], v[120:121], v[44:45], v[236:237]
	s_waitcnt lgkmcnt(6)
	v_mfma_f32_16x16x32_bf16 v[64:67], v[60:63], v[244:247], 0
	s_waitcnt lgkmcnt(4)
	v_mfma_f32_16x16x32_bf16 v[60:63], v[60:63], v[228:231], 0
	s_waitcnt lgkmcnt(2)
	v_mfma_f32_16x16x32_bf16 v[64:67], v[48:51], v[150:153], v[64:67]
	s_waitcnt lgkmcnt(0)
	s_barrier
	s_waitcnt lgkmcnt(0)
	v_mfma_f32_16x16x32_bf16 v[48:51], v[48:51], v[240:243], v[60:63]
	ds_read_b128 v[240:243], v183
	s_nop 4
	v_pk_mul_f32 v[66:67], v[58:59], v[66:67]
	v_pk_mul_f32 v[64:65], v[56:57], v[64:65]
	v_pk_fma_f32 v[128:129], v[128:129], v[46:47], v[66:67]
	v_pk_fma_f32 v[124:125], v[124:125], v[44:45], v[64:65]
	s_nop 7
	v_pk_mul_f32 v[48:49], v[56:57], v[48:49]
	v_pk_mul_f32 v[50:51], v[58:59], v[50:51]
	v_pk_fma_f32 v[130:131], v[130:131], v[44:45], v[48:49]
	v_mul_f32_e32 v44, v33, v33
	v_mul_f32_e32 v45, v35, v35
	v_fmac_f32_e32 v44, v32, v32
	v_fmac_f32_e32 v45, v34, v34
	v_pk_fma_f32 v[132:133], v[132:133], v[46:47], v[50:51]
	v_add_f32_e32 v44, v44, v45
	v_mul_f32_e32 v45, v37, v37
	v_mul_f32_e32 v46, v39, v39
	v_fmac_f32_e32 v45, v36, v36
	v_fmac_f32_e32 v46, v38, v38
	v_add_f32_e32 v45, v45, v46
	v_add_f32_e32 v44, v44, v45
	v_mul_f32_e32 v45, v53, v53
	v_mul_f32_e32 v46, v55, v55
	v_fmac_f32_e32 v45, v52, v52
	v_fmac_f32_e32 v46, v54, v54
	v_add_f32_e32 v45, v45, v46
	v_add_f32_e32 v44, v44, v45
	v_mul_f32_e32 v45, v41, v41
	v_mul_f32_e32 v46, v43, v43
	v_fmac_f32_e32 v45, v40, v40
	v_fmac_f32_e32 v46, v42, v42
	v_add_f32_e32 v45, v45, v46
	v_and_b32_e32 v46, 64, v210
	v_add_f32_e32 v44, v44, v45
	v_xor_b32_e32 v45, 16, v210
	v_add_u32_e32 v46, 64, v46
	v_cmp_lt_i32_e32 vcc, v45, v46
	s_nop 1
	v_cndmask_b32_e32 v45, v210, v45, vcc
	v_lshlrev_b32_e32 v249, 2, v45
	ds_bpermute_b32 v45, v249, v44
	s_waitcnt lgkmcnt(1)
	v_pk_mul_f32 v[50:51], v[104:105], v[242:243]
	v_pk_mul_f32 v[56:57], v[102:103], v[240:241]
	v_cvt_pk_bf16_f32 v56, v56, v57
	v_cvt_pk_bf16_f32 v57, v50, v51
	ds_write_b64 v223, v[56:57]
	s_waitcnt lgkmcnt(1)
	v_add_f32_e32 v44, v44, v45
	v_xor_b32_e32 v45, 32, v210
	v_cmp_lt_i32_e32 vcc, v45, v46
	s_nop 1
	v_cndmask_b32_e32 v45, v210, v45, vcc
	v_pk_mul_f32 v[50:51], v[114:115], v[242:243]
	v_pk_mul_f32 v[56:57], v[108:109], v[240:241]
	v_lshlrev_b32_e32 v250, 2, v45
	v_cvt_pk_bf16_f32 v56, v56, v57
	v_cvt_pk_bf16_f32 v57, v50, v51
	ds_write_b64 v223, v[56:57] offset:4352
	v_pk_mul_f32 v[50:51], v[112:113], v[242:243]
	v_pk_mul_f32 v[56:57], v[106:107], v[240:241]
	ds_bpermute_b32 v45, v250, v44
	v_cvt_pk_bf16_f32 v56, v56, v57
	v_cvt_pk_bf16_f32 v57, v50, v51
	ds_write_b64 v223, v[56:57] offset:8704
	v_pk_mul_f32 v[50:51], v[118:119], v[242:243]
	v_pk_mul_f32 v[56:57], v[110:111], v[240:241]
	s_nop 0
	v_cvt_pk_bf16_f32 v56, v56, v57
	v_cvt_pk_bf16_f32 v57, v50, v51
	ds_write_b64 v223, v[56:57] offset:13056
	v_pk_mul_f32 v[50:51], v[122:123], v[242:243]
	v_pk_mul_f32 v[56:57], v[116:117], v[240:241]
	s_nop 0
	v_cvt_pk_bf16_f32 v56, v56, v57
	v_cvt_pk_bf16_f32 v57, v50, v51
	ds_write_b64 v223, v[56:57] offset:17408
	v_pk_mul_f32 v[50:51], v[126:127], v[242:243]
	v_pk_mul_f32 v[56:57], v[120:121], v[240:241]
	s_nop 0
	v_cvt_pk_bf16_f32 v56, v56, v57
	v_cvt_pk_bf16_f32 v57, v50, v51
	ds_write_b64 v223, v[56:57] offset:21760
	v_pk_mul_f32 v[50:51], v[128:129], v[242:243]
	v_pk_mul_f32 v[56:57], v[124:125], v[240:241]
	v_pk_mul_f32 v[48:49], v[132:133], v[242:243]
	v_pk_mul_f32 v[46:47], v[130:131], v[240:241]
	v_cvt_pk_bf16_f32 v56, v56, v57
	v_cvt_pk_bf16_f32 v57, v50, v51
	v_cvt_pk_bf16_f32 v46, v46, v47
	v_cvt_pk_bf16_f32 v47, v48, v49
	ds_write_b64 v223, v[56:57] offset:26112
	ds_write_b64 v223, v[46:47] offset:30464
	s_and_saveexec_b64 s[72:73], s[16:17]
	s_cbranch_execz .LBB0_527
	s_waitcnt lgkmcnt(6)
	v_add_f32_e32 v44, v44, v45
	ds_write_b32 v184, v44
